# mixer A: next unit's K/V staging loads issued at the loop top (before QK) instead of after it; only the two Q loads stay behind QK
# speedup vs baseline: 1.0345x; 1.0150x over previous
; #define LAS __attribute__((address_space(3)))
; __device__ __forceinline__ void a_prefetch(const bf16* P, int un, int tid, int wave, int fr, int fq, v4u (&vpre)[4], bf16x8& Q0, bf16x8& Q1, bf16x8 (&K)[9][2]) {
;     int s0, sh, r, n, u0, hd; a_decode(un, s0, sh, r, n, u0, hd);
; #pragma unroll
;     for (int i = 0; i < 4; ++i) { const int e = tid + i * NTHREADS, kl = e >> 3, chunk = e & 7; int up = u0 - 64 + kl; up = up < 0 ? 0 : up; up = up > n - 1 ? n - 1 : up;
;         vpre[i] = *(const v4u*)(P + (size_t)(s0 + (up << sh) + r) * DIN + C_VA + hd * 64 + chunk * 8); }
;     { const int u = u0 + 16 * wave + fr; const bf16* qp = P + (size_t)(s0 + (u << sh) + r) * DIN + C_QA + hd * 64 + fq * 8; Q0 = *(const bf16x8*)qp; Q1 = *(const bf16x8*)(qp + 32); }
;     const int ub = u0 + 16 * wave - 64;
; #pragma unroll
;     for (int kt = 0; kt < 9; ++kt) { int up = ub + 16 * kt + fr; up = up < 0 ? 0 : up; up = up > n - 1 ? n - 1 : up;
;         const bf16* kp = P + (size_t)(s0 + (up << sh) + r) * DIN + C_KA + hd * 64 + fq * 8; K[kt][0] = *(const bf16x8*)kp; K[kt][1] = *(const bf16x8*)(kp + 32); }
; }
; __device__ __forceinline__ void mixA_mfma(const bf16* P, bf16* OG, float* LSE, LAS unsigned char* lds, int bid, int G, int tid) {
;     ...
;     for (int un = bid; un < NU; un += G) {
;         int s0, sh, r, n, u0, hd; a_decode(un, s0, sh, r, n, u0, hd);
;         const float slope = exp2f(-8.0f * (float)(hd + 1) / 12.0f) * (float)(1 << sh) * L2E;
;         __syncthreads();
; #pragma unroll
;         for (int i = 0; i < 4; ++i) { const int e = tid + i * NTHREADS; *(LAS v4u*)(Vs + (e >> 3) * VROW + (e & 7) * 16) = vpre[i]; }
;         __syncthreads();
.LBB0_333:
	s_mul_hi_i32 s14, s78, 0x2aaaaaab
	s_lshr_b32 s15, s14, 31
	s_ashr_i32 s14, s14, 1
	s_waitcnt vmcnt(5)
	s_barrier
	ds_write_b128 v176, v[2:5]
	ds_write_b128 v177, v[6:9]
	ds_write_b128 v176, v[10:13] offset:20480
	ds_write_b128 v178, v[14:17]
	ds_write_b128 v176, v[240:243] offset:40960
	ds_write_b128 v177, v[244:247] offset:40960
	ds_write_b128 v176, v[248:251] offset:61440
	ds_write_b128 v178, v[252:255] offset:40960
	s_waitcnt lgkmcnt(0)
	s_barrier
	s_add_i32 s35, s78, s68
	s_cmpk_gt_i32 s35, 0x8ff
	s_cbranch_scc1 .Lamv_skip_0
	s_mul_hi_i32 s18, s35, 0x2aaaaaab
	s_lshr_b32 s19, s18, 31
	s_ashr_i32 s18, s18, 1
	s_add_i32 s18, s18, s19
	s_mul_i32 s19, s18, -12
	s_add_i32 s19, s35, s19
	s_lshl_b32 s24, s18, 7
	s_cmpk_lt_i32 s35, 0x600
	s_cselect_b32 s25, s3, 0x7ffff000
	s_cselect_b32 s36, s12, 0x1000
	s_and_b32 s25, s25, s24
	s_ashr_i32 s19, s19, 1
	s_sub_i32 s24, s24, s25
	s_and_b32 s37, s19, -2
	s_ashr_i32 s24, s24, 7
	s_lshl_b32 s19, -1, s37
	s_andn2_b32 s19, s24, s19
	s_ashr_i32 s24, s24, s37
	s_lshl_b32 s38, s24, 7
	s_sub_i32 s39, s38, 64
	s_add_i32 s38, s38, s22
	v_add_u32_e32 v92, s38, v167
	s_lshr_b32 s36, s36, s37
	v_add_u32_e32 v2, s39, v1
	v_add_u32_e32 v4, s39, v164
	v_add_u32_e32 v10, s39, v165
	v_add_u32_e32 v12, s39, v166
	v_max_i32_e32 v26, 0, v92
	v_add_u32_e32 v34, 16, v92
	v_add_u32_e32 v42, 32, v92
	v_add_u32_e32 v50, 48, v92
	v_add_u32_e32 v58, 64, v92
	v_add_u32_e32 v66, 0x50, v92
	v_add_u32_e32 v74, 0x60, v92
	v_add_u32_e32 v82, 0x70, v92
	v_add_u32_e32 v92, 0x80, v92
	s_add_i32 s36, s36, -1
	v_max_i32_e32 v2, 0, v2
	v_max_i32_e32 v4, 0, v4
	v_max_i32_e32 v10, 0, v10
	v_max_i32_e32 v12, 0, v12
	v_max_i32_e32 v34, 0, v34
	v_max_i32_e32 v42, 0, v42
	v_max_i32_e32 v50, 0, v50
	v_max_i32_e32 v58, 0, v58
	v_max_i32_e32 v66, 0, v66
	v_max_i32_e32 v74, 0, v74
	v_max_i32_e32 v82, 0, v82
	v_max_i32_e32 v92, 0, v92
	s_add_i32 s40, s19, s25
	s_mulk_i32 s18, 0xfd00
	s_add_i32 s19, s27, s29
	v_min_i32_e32 v2, s36, v2
	v_min_i32_e32 v4, s36, v4
	v_min_i32_e32 v10, s36, v10
	v_min_i32_e32 v12, s36, v12
	v_or_b32_e32 v202, s38, v207
	v_min_i32_e32 v26, s36, v26
	v_min_i32_e32 v34, s36, v34
	v_min_i32_e32 v42, s36, v42
	v_min_i32_e32 v50, s36, v50
	v_min_i32_e32 v58, s36, v58
	v_min_i32_e32 v66, s36, v66
	v_min_i32_e32 v74, s36, v74
	v_min_i32_e32 v82, s36, v82
	v_min_i32_e32 v92, s36, v92
	s_add_i32 s18, s19, s18
	v_lshlrev_b32_e32 v2, s37, v2
	v_lshlrev_b32_e32 v4, s37, v4
	v_lshlrev_b32_e32 v10, s37, v10
	v_lshlrev_b32_e32 v12, s37, v12
	v_lshlrev_b32_e32 v202, s37, v202
	v_lshlrev_b32_e32 v26, s37, v26
	v_lshlrev_b32_e32 v34, s37, v34
	v_lshlrev_b32_e32 v42, s37, v42
	v_lshlrev_b32_e32 v50, s37, v50
	v_lshlrev_b32_e32 v58, s37, v58
	v_lshlrev_b32_e32 v66, s37, v66
	v_lshlrev_b32_e32 v74, s37, v74
	v_lshlrev_b32_e32 v82, s37, v82
	v_lshlrev_b32_e32 v92, s37, v92
	s_ashr_i32 s19, s18, 31
	v_add_u32_e32 v2, s40, v2
	v_mov_b64_e32 v[90:91], s[74:75]
	v_add_u32_e32 v4, s40, v4
	v_add_u32_e32 v10, s40, v10
	v_add_u32_e32 v12, s40, v12
	v_add_u32_e32 v202, s40, v202
	v_add_u32_e32 v26, s40, v26
	v_add_u32_e32 v34, s40, v34
	v_add_u32_e32 v42, s40, v42
	v_add_u32_e32 v50, s40, v50
	v_add_u32_e32 v58, s40, v58
	v_add_u32_e32 v66, s40, v66
	v_add_u32_e32 v74, s40, v74
	v_add_u32_e32 v82, s40, v82
	v_add_u32_e32 v92, s40, v92
	v_mad_i64_i32 v[2:3], s[24:25], v2, s13, v[90:91]
	s_lshl_b64 s[18:19], s[18:19], 1
	v_mad_i64_i32 v[4:5], s[24:25], v4, s13, v[90:91]
	v_mad_i64_i32 v[10:11], s[24:25], v10, s13, v[90:91]
	v_mad_i64_i32 v[12:13], s[24:25], v12, s13, v[90:91]
	v_mad_i64_i32 v[202:203], s[24:25], v202, s13, v[90:91]
	v_mad_i64_i32 v[26:27], s[24:25], v26, s13, v[90:91]
	v_mad_i64_i32 v[34:35], s[24:25], v34, s13, v[90:91]
	v_mad_i64_i32 v[42:43], s[24:25], v42, s13, v[90:91]
	v_mad_i64_i32 v[50:51], s[24:25], v50, s13, v[90:91]
	v_mad_i64_i32 v[58:59], s[24:25], v58, s13, v[90:91]
	v_mad_i64_i32 v[66:67], s[24:25], v66, s13, v[90:91]
	v_mad_i64_i32 v[74:75], s[24:25], v74, s13, v[90:91]
	v_mad_i64_i32 v[82:83], s[24:25], v82, s13, v[90:91]
	v_mad_i64_i32 v[90:91], s[24:25], v92, s13, v[90:91]
	v_lshl_add_u64 v[2:3], v[2:3], 0, s[18:19]
	v_mov_b32_e32 v159, v135
	v_lshl_add_u64 v[4:5], v[4:5], 0, s[18:19]
	v_lshl_add_u64 v[10:11], v[10:11], 0, s[18:19]
	v_lshl_add_u64 v[12:13], v[12:13], 0, s[18:19]
	v_lshl_add_u64 v[202:203], v[202:203], 0, s[18:19]
	v_mov_b32_e32 v161, v135
	v_lshl_add_u64 v[26:27], v[26:27], 0, s[18:19]
	v_lshl_add_u64 v[34:35], v[34:35], 0, s[18:19]
	v_lshl_add_u64 v[42:43], v[42:43], 0, s[18:19]
	v_lshl_add_u64 v[50:51], v[50:51], 0, s[18:19]
	v_lshl_add_u64 v[58:59], v[58:59], 0, s[18:19]
	v_lshl_add_u64 v[66:67], v[66:67], 0, s[18:19]
	v_lshl_add_u64 v[74:75], v[74:75], 0, s[18:19]
	v_lshl_add_u64 v[82:83], v[82:83], 0, s[18:19]
	v_lshl_add_u64 v[90:91], v[90:91], 0, s[18:19]
	v_lshl_add_u64 v[2:3], v[2:3], 0, v[158:159]
	v_lshl_add_u64 v[6:7], v[4:5], 0, v[158:159]
	v_lshl_add_u64 v[10:11], v[10:11], 0, v[158:159]
	v_lshl_add_u64 v[14:15], v[12:13], 0, v[158:159]
	v_lshl_add_u64 v[204:205], v[202:203], 0, v[160:161]
	v_lshl_add_u64 v[30:31], v[26:27], 0, v[160:161]
	v_lshl_add_u64 v[38:39], v[34:35], 0, v[160:161]
	v_lshl_add_u64 v[46:47], v[42:43], 0, v[160:161]
	v_lshl_add_u64 v[54:55], v[50:51], 0, v[160:161]
	v_lshl_add_u64 v[62:63], v[58:59], 0, v[160:161]
	v_lshl_add_u64 v[70:71], v[66:67], 0, v[160:161]
	v_lshl_add_u64 v[78:79], v[74:75], 0, v[160:161]
	v_lshl_add_u64 v[86:87], v[82:83], 0, v[160:161]
	v_lshl_add_u64 v[94:95], v[90:91], 0, v[160:161]
	global_load_dwordx4 v[240:243], v[2:3], off offset:1536
	global_load_dwordx4 v[244:247], v[6:7], off offset:1536
	global_load_dwordx4 v[248:251], v[10:11], off offset:1536
	global_load_dwordx4 v[252:255], v[14:15], off offset:1536
	global_load_dwordx4 v[2:5], v[2:3], off offset:3072
	s_nop 0
	global_load_dwordx4 v[6:9], v[6:7], off offset:3072
	s_nop 0
	global_load_dwordx4 v[10:13], v[10:11], off offset:3072
	s_nop 0
	global_load_dwordx4 v[14:17], v[14:15], off offset:3072
	s_nop 0
	s_nop 0
; __device__ __forceinline__ void mixA_mfma(const bf16* P, bf16* OG, float* LSE, LAS unsigned char* lds, int bid, int G, int tid) {
;     ...
;         const int u = u0 + 16 * wave + fr;
;         const size_t qrow = (size_t)(s0 + (u << sh) + r);
;         f32x4 S[10];
;         const int ub = u0 + 16 * wave - 64;
; #pragma unroll
;         for (int kt = 0; kt < 9; ++kt) { f32x4 z = {0.f, 0.f, 0.f, 0.f};
;             z = __builtin_amdgcn_mfma_f32_16x16x32_bf16(Kn[kt][0], Qn0, z, 0, 0, 0);
;             S[kt] = __builtin_amdgcn_mfma_f32_16x16x32_bf16(Kn[kt][1], Qn1, z, 0, 0, 0); }
;         asm volatile("" ::: "memory");
;         if (un + G < NU) a_prefetch(P, un + G, tid, wave, fr, fq, vpre, Qn0, Qn1, Kn);
.Lamv_skip_0:
	ds_read_b128 v[26:29], v239 offset:40960
	ds_read_b128 v[30:33], v239 offset:41024
	ds_read_b128 v[34:37], v239 offset:43520
	ds_read_b128 v[38:41], v239 offset:43584
	ds_read_b128 v[42:45], v239 offset:46080
	ds_read_b128 v[46:49], v239 offset:46144
	ds_read_b128 v[50:53], v239 offset:48640
	ds_read_b128 v[54:57], v239 offset:48704
	ds_read_b128 v[58:61], v239 offset:51200
	ds_read_b128 v[62:65], v239 offset:51264
	ds_read_b128 v[66:69], v239 offset:53760
	ds_read_b128 v[70:73], v239 offset:53824
	ds_read_b128 v[74:77], v239 offset:56320
	ds_read_b128 v[78:81], v239 offset:56384
	s_waitcnt lgkmcnt(13)
	v_mfma_f32_16x16x32_bf16 v[98:101], v[26:29], v[18:21], 0
	s_add_i32 s15, s14, s15
	s_mul_i32 s14, s15, -12
	s_add_i32 s14, s78, s14
	s_add_i32 s16, s14, 1
	s_waitcnt lgkmcnt(12)
	v_mfma_f32_16x16x32_bf16 v[130:133], v[30:33], v[22:25], v[98:101]
	v_cvt_f32_i32_e32 v102, s16
	s_waitcnt lgkmcnt(11)
	v_mfma_f32_16x16x32_bf16 v[98:101], v[34:37], v[18:21], 0
	v_mul_f32_e32 v102, 0xc1000000, v102
	v_div_scale_f32 v103, s[16:17], s31, s31, v102
	s_waitcnt lgkmcnt(10)
	v_mfma_f32_16x16x32_bf16 v[126:129], v[38:41], v[22:25], v[98:101]
	v_rcp_f32_e32 v104, v103
	ds_read_b128 v[82:85], v239 offset:58880
	ds_read_b128 v[86:89], v239 offset:58944
	ds_read_b128 v[90:93], v239 offset:61440
	ds_read_b128 v[94:97], v239 offset:61504
	s_waitcnt lgkmcnt(13)
	v_mfma_f32_16x16x32_bf16 v[98:101], v[42:45], v[18:21], 0
	v_fma_f32 v105, -v103, v104, 1.0
	v_fmac_f32_e32 v104, v105, v104
	v_div_scale_f32 v105, vcc, v102, s31, v102
	s_waitcnt lgkmcnt(12)
	v_mfma_f32_16x16x32_bf16 v[122:125], v[46:49], v[22:25], v[98:101]
	v_mul_f32_e32 v106, v105, v104
	v_fma_f32 v107, -v103, v106, v105
	v_fmac_f32_e32 v106, v107, v104
	s_waitcnt lgkmcnt(11)
	v_mfma_f32_16x16x32_bf16 v[98:101], v[50:53], v[18:21], 0
	v_fma_f32 v103, -v103, v106, v105
	s_waitcnt lgkmcnt(10)
	v_mfma_f32_16x16x32_bf16 v[118:121], v[54:57], v[22:25], v[98:101]
	s_waitcnt lgkmcnt(9)
	v_mfma_f32_16x16x32_bf16 v[98:101], v[58:61], v[18:21], 0
	s_waitcnt lgkmcnt(8)
	v_mfma_f32_16x16x32_bf16 v[114:117], v[62:65], v[22:25], v[98:101]
	s_nop 6
	v_div_fmas_f32 v98, v103, v104, v106
	v_div_fixup_f32 v102, v98, s31, v102
	s_waitcnt lgkmcnt(7)
	v_mfma_f32_16x16x32_bf16 v[98:101], v[66:69], v[18:21], 0
	v_cmp_gt_f32_e32 vcc, s33, v102
	s_and_b64 s[16:17], vcc, exec
	s_cselect_b32 s16, 0xffffffc0, 0
	s_waitcnt lgkmcnt(6)
	v_mfma_f32_16x16x32_bf16 v[110:113], v[70:73], v[22:25], v[98:101]
	v_cndmask_b32_e32 v103, 0, v181, vcc
	v_add_f32_e32 v102, v102, v103
	v_exp_f32_e32 v102, v102
	s_waitcnt lgkmcnt(5)
	v_mfma_f32_16x16x32_bf16 v[98:101], v[74:77], v[18:21], 0
	s_add_i32 s35, s78, s68
	s_cmpk_gt_i32 s35, 0x8ff
	v_ldexp_f32 v134, v102, s16
	s_waitcnt lgkmcnt(4)
	v_mfma_f32_16x16x32_bf16 v[106:109], v[78:81], v[22:25], v[98:101]
	s_cselect_b64 s[16:17], -1, 0
	s_and_b64 vcc, exec, s[16:17]
	s_waitcnt lgkmcnt(3)
	v_mfma_f32_16x16x32_bf16 v[98:101], v[82:85], v[18:21], 0
	s_waitcnt lgkmcnt(2)
	v_mfma_f32_16x16x32_bf16 v[102:105], v[86:89], v[22:25], v[98:101]
	s_waitcnt lgkmcnt(1)
	v_mfma_f32_16x16x32_bf16 v[98:101], v[90:93], v[18:21], 0
	s_waitcnt lgkmcnt(0)
	v_mfma_f32_16x16x32_bf16 v[98:101], v[94:97], v[22:25], v[98:101]
	s_cbranch_vccnz .LBB0_335
	global_load_dwordx4 v[18:21], v[204:205], off
	global_load_dwordx4 v[22:25], v[204:205], off offset:64

; #define LAS __attribute__((address_space(3)))
; __device__ __forceinline__ void a_prefetch(const bf16* P, int un, int tid, int wave, int fr, int fq, v4u (&vpre)[4], bf16x8& Q0, bf16x8& Q1, bf16x8 (&K)[9][2]) {
;     int s0, sh, r, n, u0, hd; a_decode(un, s0, sh, r, n, u0, hd);
; #pragma unroll
;     for (int i = 0; i < 4; ++i) { const int e = tid + i * NTHREADS, kl = e >> 3, chunk = e & 7; int up = u0 - 64 + kl; up = up < 0 ? 0 : up; up = up > n - 1 ? n - 1 : up;
;         vpre[i] = *(const v4u*)(P + (size_t)(s0 + (up << sh) + r) * DIN + C_VA + hd * 64 + chunk * 8); }
;     { const int u = u0 + 16 * wave + fr; const bf16* qp = P + (size_t)(s0 + (u << sh) + r) * DIN + C_QA + hd * 64 + fq * 8; Q0 = *(const bf16x8*)qp; Q1 = *(const bf16x8*)(qp + 32); }
;     const int ub = u0 + 16 * wave - 64;
; #pragma unroll
;     for (int kt = 0; kt < 9; ++kt) { int up = ub + 16 * kt + fr; up = up < 0 ? 0 : up; up = up > n - 1 ? n - 1 : up;
;         const bf16* kp = P + (size_t)(s0 + (up << sh) + r) * DIN + C_KA + hd * 64 + fq * 8; K[kt][0] = *(const bf16x8*)kp; K[kt][1] = *(const bf16x8*)(kp + 32); }
; }
; __device__ __forceinline__ void mixA_mfma(const bf16* P, bf16* OG, float* LSE, LAS unsigned char* lds, int bid, int G, int tid) {
;     ...
;     for (int un = bid; un < NU; un += G) {
;         int s0, sh, r, n, u0, hd; a_decode(un, s0, sh, r, n, u0, hd);
;         const float slope = exp2f(-8.0f * (float)(hd + 1) / 12.0f) * (float)(1 << sh) * L2E;
;         __syncthreads();
; #pragma unroll
;         for (int i = 0; i < 4; ++i) { const int e = tid + i * NTHREADS; *(LAS v4u*)(Vs + (e >> 3) * VROW + (e & 7) * 16) = vpre[i]; }
;         __syncthreads();
.LBB0_1358:
	s_mul_hi_i32 s14, s33, 0x2aaaaaab
	s_lshr_b32 s15, s14, 31
	s_ashr_i32 s14, s14, 1
	s_waitcnt vmcnt(5)
	s_barrier
	ds_write_b128 v176, v[2:5]
	ds_write_b128 v177, v[6:9]
	ds_write_b128 v176, v[10:13] offset:20480
	ds_write_b128 v178, v[14:17]
	ds_write_b128 v176, v[240:243] offset:40960
	ds_write_b128 v177, v[244:247] offset:40960
	ds_write_b128 v176, v[248:251] offset:61440
	ds_write_b128 v178, v[252:255] offset:40960
	s_waitcnt lgkmcnt(0)
	s_barrier
	s_add_i32 s31, s33, s68
	s_cmpk_gt_i32 s31, 0x8ff
	s_cbranch_scc1 .Lamv_skip_1
	s_mul_hi_i32 s18, s31, 0x2aaaaaab
	s_lshr_b32 s19, s18, 31
	s_ashr_i32 s18, s18, 1
	s_add_i32 s18, s18, s19
	s_mul_i32 s19, s18, -12
	s_add_i32 s19, s31, s19
	s_lshl_b32 s35, s18, 7
	s_cmpk_lt_i32 s31, 0x600
	s_cselect_b32 s40, s12, 0x7ffff000
	s_cselect_b32 s41, s13, 0x1000
	s_and_b32 s40, s40, s35
	s_ashr_i32 s19, s19, 1
	s_sub_i32 s35, s35, s40
	s_and_b32 s42, s19, -2
	s_ashr_i32 s35, s35, 7
	s_lshl_b32 s19, -1, s42
	s_andn2_b32 s19, s35, s19
	s_ashr_i32 s35, s35, s42
	s_lshl_b32 s35, s35, 7
	s_sub_i32 s43, s35, 64
	s_add_i32 s35, s35, s21
	v_add_u32_e32 v92, s35, v167
	s_lshr_b32 s41, s41, s42
	v_add_u32_e32 v2, s43, v1
	v_add_u32_e32 v4, s43, v164
	v_add_u32_e32 v10, s43, v165
	v_add_u32_e32 v12, s43, v166
	v_max_i32_e32 v26, 0, v92
	v_add_u32_e32 v34, 16, v92
	v_add_u32_e32 v42, 32, v92
	v_add_u32_e32 v50, 48, v92
	v_add_u32_e32 v58, 64, v92
	v_add_u32_e32 v66, 0x50, v92
	v_add_u32_e32 v74, 0x60, v92
	v_add_u32_e32 v82, 0x70, v92
	v_add_u32_e32 v92, 0x80, v92
	s_add_i32 s50, s41, -1
	v_max_i32_e32 v2, 0, v2
	v_max_i32_e32 v4, 0, v4
	v_max_i32_e32 v10, 0, v10
	v_max_i32_e32 v12, 0, v12
	v_max_i32_e32 v34, 0, v34
	v_max_i32_e32 v42, 0, v42
	v_max_i32_e32 v50, 0, v50
	v_max_i32_e32 v58, 0, v58
	v_max_i32_e32 v66, 0, v66
	v_max_i32_e32 v74, 0, v74
	v_max_i32_e32 v82, 0, v82
	v_max_i32_e32 v92, 0, v92
	s_add_i32 s51, s19, s40
	s_mulk_i32 s18, 0xfd00
	s_add_i32 s19, s24, s25
	v_min_i32_e32 v2, s50, v2
	v_min_i32_e32 v4, s50, v4
	v_min_i32_e32 v10, s50, v10
	v_min_i32_e32 v12, s50, v12
	v_or_b32_e32 v202, s35, v213
	v_min_i32_e32 v26, s50, v26
	v_min_i32_e32 v34, s50, v34
	v_min_i32_e32 v42, s50, v42
	v_min_i32_e32 v50, s50, v50
	v_min_i32_e32 v58, s50, v58
	v_min_i32_e32 v66, s50, v66
	v_min_i32_e32 v74, s50, v74
	v_min_i32_e32 v82, s50, v82
	v_min_i32_e32 v92, s50, v92
	s_add_i32 s18, s19, s18
	v_lshlrev_b32_e32 v2, s42, v2
	v_lshlrev_b32_e32 v4, s42, v4
	v_lshlrev_b32_e32 v10, s42, v10
	v_lshlrev_b32_e32 v12, s42, v12
	v_lshlrev_b32_e32 v202, s42, v202
	v_lshlrev_b32_e32 v26, s42, v26
	v_lshlrev_b32_e32 v34, s42, v34
	v_lshlrev_b32_e32 v42, s42, v42
	v_lshlrev_b32_e32 v50, s42, v50
	v_lshlrev_b32_e32 v58, s42, v58
	v_lshlrev_b32_e32 v66, s42, v66
	v_lshlrev_b32_e32 v74, s42, v74
	v_lshlrev_b32_e32 v82, s42, v82
	v_lshlrev_b32_e32 v92, s42, v92
	s_ashr_i32 s19, s18, 31
	v_add_u32_e32 v2, s51, v2
	v_mov_b64_e32 v[90:91], s[74:75]
	v_add_u32_e32 v4, s51, v4
	v_add_u32_e32 v10, s51, v10
	v_add_u32_e32 v12, s51, v12
	v_add_u32_e32 v202, s51, v202
	v_add_u32_e32 v26, s51, v26
	v_add_u32_e32 v34, s51, v34
	v_add_u32_e32 v42, s51, v42
	v_add_u32_e32 v50, s51, v50
	v_add_u32_e32 v58, s51, v58
	v_add_u32_e32 v66, s51, v66
	v_add_u32_e32 v74, s51, v74
	v_add_u32_e32 v82, s51, v82
	v_add_u32_e32 v92, s51, v92
	v_mad_i64_i32 v[2:3], s[40:41], v2, s20, v[90:91]
	s_lshl_b64 s[18:19], s[18:19], 1
	v_mad_i64_i32 v[4:5], s[40:41], v4, s20, v[90:91]
	v_mad_i64_i32 v[10:11], s[40:41], v10, s20, v[90:91]
	v_mad_i64_i32 v[12:13], s[40:41], v12, s20, v[90:91]
	v_mad_i64_i32 v[202:203], s[40:41], v202, s20, v[90:91]
	v_mad_i64_i32 v[26:27], s[40:41], v26, s20, v[90:91]
	v_mad_i64_i32 v[34:35], s[40:41], v34, s20, v[90:91]
	v_mad_i64_i32 v[42:43], s[40:41], v42, s20, v[90:91]
	v_mad_i64_i32 v[50:51], s[40:41], v50, s20, v[90:91]
	v_mad_i64_i32 v[58:59], s[40:41], v58, s20, v[90:91]
	v_mad_i64_i32 v[66:67], s[40:41], v66, s20, v[90:91]
	v_mad_i64_i32 v[74:75], s[40:41], v74, s20, v[90:91]
	v_mad_i64_i32 v[82:83], s[40:41], v82, s20, v[90:91]
	v_mad_i64_i32 v[90:91], s[40:41], v92, s20, v[90:91]
	v_lshl_add_u64 v[2:3], v[2:3], 0, s[18:19]
	v_mov_b32_e32 v159, v135
	v_lshl_add_u64 v[4:5], v[4:5], 0, s[18:19]
	v_lshl_add_u64 v[10:11], v[10:11], 0, s[18:19]
	v_lshl_add_u64 v[12:13], v[12:13], 0, s[18:19]
	v_lshl_add_u64 v[202:203], v[202:203], 0, s[18:19]
	v_mov_b32_e32 v161, v135
	v_lshl_add_u64 v[26:27], v[26:27], 0, s[18:19]
	v_lshl_add_u64 v[34:35], v[34:35], 0, s[18:19]
	v_lshl_add_u64 v[42:43], v[42:43], 0, s[18:19]
	v_lshl_add_u64 v[50:51], v[50:51], 0, s[18:19]
	v_lshl_add_u64 v[58:59], v[58:59], 0, s[18:19]
	v_lshl_add_u64 v[66:67], v[66:67], 0, s[18:19]
	v_lshl_add_u64 v[74:75], v[74:75], 0, s[18:19]
	v_lshl_add_u64 v[82:83], v[82:83], 0, s[18:19]
	v_lshl_add_u64 v[90:91], v[90:91], 0, s[18:19]
	v_lshl_add_u64 v[2:3], v[2:3], 0, v[158:159]
	v_lshl_add_u64 v[6:7], v[4:5], 0, v[158:159]
	v_lshl_add_u64 v[10:11], v[10:11], 0, v[158:159]
	v_lshl_add_u64 v[14:15], v[12:13], 0, v[158:159]
	v_lshl_add_u64 v[204:205], v[202:203], 0, v[160:161]
	v_lshl_add_u64 v[30:31], v[26:27], 0, v[160:161]
	v_lshl_add_u64 v[38:39], v[34:35], 0, v[160:161]
	v_lshl_add_u64 v[46:47], v[42:43], 0, v[160:161]
	v_lshl_add_u64 v[54:55], v[50:51], 0, v[160:161]
	v_lshl_add_u64 v[62:63], v[58:59], 0, v[160:161]
	v_lshl_add_u64 v[70:71], v[66:67], 0, v[160:161]
	v_lshl_add_u64 v[78:79], v[74:75], 0, v[160:161]
	v_lshl_add_u64 v[86:87], v[82:83], 0, v[160:161]
	v_lshl_add_u64 v[94:95], v[90:91], 0, v[160:161]
	global_load_dwordx4 v[240:243], v[2:3], off offset:1536
	global_load_dwordx4 v[244:247], v[6:7], off offset:1536
	global_load_dwordx4 v[248:251], v[10:11], off offset:1536
	global_load_dwordx4 v[252:255], v[14:15], off offset:1536
	global_load_dwordx4 v[2:5], v[2:3], off offset:3072
	s_nop 0
	global_load_dwordx4 v[6:9], v[6:7], off offset:3072
	s_nop 0
	global_load_dwordx4 v[10:13], v[10:11], off offset:3072
	s_nop 0
	global_load_dwordx4 v[14:17], v[14:15], off offset:3072
	s_nop 0
	s_nop 0
; __device__ __forceinline__ void mixA_mfma(const bf16* P, bf16* OG, float* LSE, LAS unsigned char* lds, int bid, int G, int tid) {
;     ...
;         const int u = u0 + 16 * wave + fr;
;         const size_t qrow = (size_t)(s0 + (u << sh) + r);
;         f32x4 S[10];
;         const int ub = u0 + 16 * wave - 64;
; #pragma unroll
;         for (int kt = 0; kt < 9; ++kt) { f32x4 z = {0.f, 0.f, 0.f, 0.f};
;             z = __builtin_amdgcn_mfma_f32_16x16x32_bf16(Kn[kt][0], Qn0, z, 0, 0, 0);
;             S[kt] = __builtin_amdgcn_mfma_f32_16x16x32_bf16(Kn[kt][1], Qn1, z, 0, 0, 0); }
;         asm volatile("" ::: "memory");
;         if (un + G < NU) a_prefetch(P, un + G, tid, wave, fr, fq, vpre, Qn0, Qn1, Kn);
.Lamv_skip_1:
	ds_read_b128 v[26:29], v239 offset:40960
	ds_read_b128 v[30:33], v239 offset:41024
	ds_read_b128 v[34:37], v239 offset:43520
	ds_read_b128 v[38:41], v239 offset:43584
	ds_read_b128 v[42:45], v239 offset:46080
	ds_read_b128 v[46:49], v239 offset:46144
	ds_read_b128 v[50:53], v239 offset:48640
	ds_read_b128 v[54:57], v239 offset:48704
	ds_read_b128 v[58:61], v239 offset:51200
	ds_read_b128 v[62:65], v239 offset:51264
	ds_read_b128 v[66:69], v239 offset:53760
	ds_read_b128 v[70:73], v239 offset:53824
	ds_read_b128 v[74:77], v239 offset:56320
	ds_read_b128 v[78:81], v239 offset:56384
	s_waitcnt lgkmcnt(13)
	v_mfma_f32_16x16x32_bf16 v[98:101], v[26:29], v[18:21], 0
	s_add_i32 s15, s14, s15
	s_mul_i32 s14, s15, -12
	s_add_i32 s14, s33, s14
	s_add_i32 s16, s14, 1
	s_waitcnt lgkmcnt(12)
	v_mfma_f32_16x16x32_bf16 v[130:133], v[30:33], v[22:25], v[98:101]
	v_cvt_f32_i32_e32 v102, s16
	s_waitcnt lgkmcnt(11)
	v_mfma_f32_16x16x32_bf16 v[98:101], v[34:37], v[18:21], 0
	v_mul_f32_e32 v102, 0xc1000000, v102
	v_div_scale_f32 v103, s[16:17], s26, s26, v102
	s_waitcnt lgkmcnt(10)
	v_mfma_f32_16x16x32_bf16 v[126:129], v[38:41], v[22:25], v[98:101]
	v_rcp_f32_e32 v104, v103
	ds_read_b128 v[82:85], v239 offset:58880
	ds_read_b128 v[86:89], v239 offset:58944
	ds_read_b128 v[90:93], v239 offset:61440
	ds_read_b128 v[94:97], v239 offset:61504
	s_waitcnt lgkmcnt(13)
	v_mfma_f32_16x16x32_bf16 v[98:101], v[42:45], v[18:21], 0
	v_fma_f32 v105, -v103, v104, 1.0
	v_fmac_f32_e32 v104, v105, v104
	v_div_scale_f32 v105, vcc, v102, s26, v102
	s_waitcnt lgkmcnt(12)
	v_mfma_f32_16x16x32_bf16 v[122:125], v[46:49], v[22:25], v[98:101]
	v_mul_f32_e32 v106, v105, v104
	v_fma_f32 v107, -v103, v106, v105
	v_fmac_f32_e32 v106, v107, v104
	s_waitcnt lgkmcnt(11)
	v_mfma_f32_16x16x32_bf16 v[98:101], v[50:53], v[18:21], 0
	v_fma_f32 v103, -v103, v106, v105
	s_waitcnt lgkmcnt(10)
	v_mfma_f32_16x16x32_bf16 v[118:121], v[54:57], v[22:25], v[98:101]
	s_waitcnt lgkmcnt(9)
	v_mfma_f32_16x16x32_bf16 v[98:101], v[58:61], v[18:21], 0
	s_waitcnt lgkmcnt(8)
	v_mfma_f32_16x16x32_bf16 v[114:117], v[62:65], v[22:25], v[98:101]
	s_nop 5
	v_div_fmas_f32 v98, v103, v104, v106
	v_div_fixup_f32 v102, v98, s26, v102
	s_waitcnt lgkmcnt(7)
	v_mfma_f32_16x16x32_bf16 v[98:101], v[66:69], v[18:21], 0
	v_cmp_gt_f32_e32 vcc, s27, v102
	s_and_b64 s[16:17], vcc, exec
	s_cselect_b32 s16, 0xffffffc0, 0
	s_waitcnt lgkmcnt(6)
	v_mfma_f32_16x16x32_bf16 v[110:113], v[70:73], v[22:25], v[98:101]
	v_cndmask_b32_e32 v103, 0, v181, vcc
	v_add_f32_e32 v102, v102, v103
	v_exp_f32_e32 v102, v102
	s_waitcnt lgkmcnt(5)
	v_mfma_f32_16x16x32_bf16 v[98:101], v[74:77], v[18:21], 0
	s_add_i32 s31, s33, s68
	s_cmpk_gt_i32 s31, 0x8ff
	v_ldexp_f32 v134, v102, s16
	s_waitcnt lgkmcnt(4)
	v_mfma_f32_16x16x32_bf16 v[106:109], v[78:81], v[22:25], v[98:101]
	s_cselect_b64 s[16:17], -1, 0
	s_and_b64 vcc, exec, s[16:17]
	s_waitcnt lgkmcnt(3)
	v_mfma_f32_16x16x32_bf16 v[98:101], v[82:85], v[18:21], 0
	s_waitcnt lgkmcnt(2)
	v_mfma_f32_16x16x32_bf16 v[102:105], v[86:89], v[22:25], v[98:101]
	s_waitcnt lgkmcnt(1)
	v_mfma_f32_16x16x32_bf16 v[98:101], v[90:93], v[18:21], 0
	s_waitcnt lgkmcnt(0)
	v_mfma_f32_16x16x32_bf16 v[98:101], v[94:97], v[22:25], v[98:101]
	s_cbranch_vccnz .LBB0_1360
	global_load_dwordx4 v[18:21], v[204:205], off
	global_load_dwordx4 v[22:25], v[204:205], off offset:64
